# token-shift norm loop: quarter-row and gain loads batched; rwkv gate loop: ln_g/ln_b/v loads issued together
# speedup vs baseline: 1.0205x; 1.0035x over previous
.Lxm_plain_4096:
	global_load_dwordx4 v[100:103], v[82:83], off
	global_load_dwordx4 v[104:107], v[82:83], off offset:1024
	global_load_dwordx4 v[108:111], v[82:83], off offset:2048
	global_load_dwordx4 v[112:115], v[82:83], off offset:3072
	global_load_dwordx4 v[128:131], v[152:153], off offset:2048
	global_load_dwordx4 v[124:127], v[152:153], off offset:3072
	global_load_dwordx4 v[120:123], v[152:153], off offset:1024
	global_load_dwordx4 v[116:119], v[152:153], off
	s_cmpk_gt_i32 s7, 0x407f
	s_waitcnt vmcnt(7)
	v_pk_mul_f32 v[180:181], v[102:103], v[102:103]
	v_pk_mul_f32 v[182:183], v[100:101], v[100:101]
	s_nop 0
	v_pk_mov_b32 v[184:185], v[182:183], v[180:181] op_sel:[1,0]
	v_mov_b32_e32 v183, v181
	v_pk_add_f32 v[186:187], v[184:185], v[182:183]
	s_waitcnt vmcnt(6)
	v_pk_mul_f32 v[188:189], v[106:107], v[106:107]
	v_pk_mul_f32 v[190:191], v[104:105], v[104:105]
	s_nop 0
	v_pk_mov_b32 v[192:193], v[190:191], v[188:189] op_sel:[1,0]
	v_mov_b32_e32 v191, v189
	v_pk_add_f32 v[194:195], v[192:193], v[190:191]
	s_nop 0
	v_pk_add_f32 v[82:83], v[186:187], v[186:187] op_sel:[0,1] op_sel_hi:[1,0]
	v_pk_add_f32 v[186:187], v[194:195], v[194:195] op_sel:[0,1] op_sel_hi:[1,0]
	s_waitcnt vmcnt(4)
	v_mul_f32_e32 v80, v112, v112
	v_mul_f32_e32 v196, v113, v113
	v_mov_b32_e32 v83, v80
	v_mov_b32_e32 v187, v196
	v_mul_f32_e32 v80, v109, v109
	v_pk_add_f32 v[82:83], v[82:83], v[186:187]
	v_pk_fma_f32 v[186:187], v[108:109], v[108:109], v[80:81] op_sel_hi:[1,1,0]
	v_mul_f32_e32 v80, v111, v111
	v_mul_f32_e32 v197, v114, v114
	v_mul_f32_e32 v198, v115, v115
	v_pk_fma_f32 v[194:195], v[110:111], v[110:111], v[80:81] op_sel_hi:[1,1,0]
	v_mov_b32_e32 v187, v197
	v_mov_b32_e32 v195, v198
	v_pk_add_f32 v[186:187], v[186:187], v[194:195]
	s_nop 0
	v_pk_add_f32 v[82:83], v[82:83], v[186:187]
	s_nop 0
	v_add_f32_e32 v80, v82, v83
	ds_bpermute_b32 v82, v149, v80
	s_waitcnt lgkmcnt(0)
	v_add_f32_e32 v80, v80, v82
	ds_bpermute_b32 v82, v171, v80
	s_waitcnt lgkmcnt(0)
	v_add_f32_e32 v80, v80, v82
	ds_bpermute_b32 v82, v172, v80
	s_waitcnt lgkmcnt(0)
	v_add_f32_e32 v80, v80, v82
	ds_bpermute_b32 v82, v173, v80
	s_waitcnt lgkmcnt(0)
	v_add_f32_e32 v80, v80, v82
	ds_bpermute_b32 v82, v174, v80
	s_waitcnt lgkmcnt(0)
	v_add_f32_e32 v80, v80, v82
	ds_bpermute_b32 v82, v175, v80
	s_waitcnt lgkmcnt(0)
	v_add_f32_e32 v80, v80, v82
	v_fmamk_f32 v80, v80, 0x3a800000, v231
	v_cmp_gt_f32_e32 vcc, s48, v80
	v_mul_f32_e32 v82, 0x4f800000, v80
	s_nop 0
	v_cndmask_b32_e32 v80, v80, v82, vcc
	v_sqrt_f32_e32 v82, v80
	s_nop 0
	v_add_u32_e32 v83, -1, v82
	v_fma_f32 v200, -v83, v82, v80
	v_cmp_ge_f32_e64 s[42:43], 0, v200
	v_add_u32_e32 v200, 1, v82
	s_nop 0
	v_cndmask_b32_e64 v83, v82, v83, s[42:43]
	v_fma_f32 v82, -v200, v82, v80
	v_cmp_lt_f32_e64 s[42:43], 0, v82
	s_nop 1
	v_cndmask_b32_e64 v82, v83, v200, s[42:43]
	v_mul_f32_e32 v83, 0x37800000, v82
	v_cndmask_b32_e32 v82, v82, v83, vcc
	v_cmp_class_f32_e32 vcc, v80, v230
	s_nop 1
	v_cndmask_b32_e32 v80, v82, v80, vcc
	v_div_scale_f32 v82, s[18:19], v80, v80, 1.0
	v_rcp_f32_e32 v83, v82
	s_nop 0
	v_fma_f32 v200, -v82, v83, 1.0
	v_fmac_f32_e32 v83, v200, v83
	v_div_scale_f32 v200, vcc, 1.0, v80, 1.0
	v_mul_f32_e32 v201, v200, v83
	v_fma_f32 v202, -v82, v201, v200
	v_fmac_f32_e32 v201, v202, v83
	v_fma_f32 v82, -v82, v201, v200
	v_div_fmas_f32 v82, v82, v83, v201
	v_div_fixup_f32 v170, v82, v80, 1.0
	v_pk_mul_f32 v[82:83], v[100:101], v[170:171] op_sel_hi:[1,0]
	v_pk_mul_f32 v[100:101], v[102:103], v[170:171] op_sel_hi:[1,0]
	s_waitcnt vmcnt(0)
	v_pk_mul_f32 v[102:103], v[118:119], v[100:101]
	v_pk_mul_f32 v[100:101], v[116:117], v[82:83]
	v_pk_mul_f32 v[82:83], v[104:105], v[170:171] op_sel_hi:[1,0]
	v_pk_mul_f32 v[104:105], v[106:107], v[170:171] op_sel_hi:[1,0]
	s_nop 0
	v_pk_mul_f32 v[106:107], v[122:123], v[104:105]
	v_pk_mul_f32 v[104:105], v[120:121], v[82:83]
	v_pk_mul_f32 v[82:83], v[108:109], v[170:171] op_sel_hi:[1,0]
	v_pk_mul_f32 v[108:109], v[110:111], v[170:171] op_sel_hi:[1,0]
	s_nop 0
	v_pk_mul_f32 v[110:111], v[130:131], v[108:109]
	v_pk_mul_f32 v[108:109], v[128:129], v[82:83]
	s_cbranch_scc0 .LBB0_3466
	s_lshl_b64 s[18:19], s[92:93], 12
	v_lshl_add_u64 v[140:141], v[154:155], 0, s[18:19]
	v_lshl_add_u64 v[82:83], v[156:157], 0, s[18:19]
	global_load_dwordx4 v[136:139], v[140:141], off
	s_nop 0
	global_store_dwordx4 v[82:83], v[100:103], off
	global_load_dwordx4 v[144:147], v[140:141], off offset:1024
	s_mov_b64 s[18:19], -1
	global_store_dwordx4 v[82:83], v[104:107], off offset:1024
	global_load_dwordx4 v[132:135], v[140:141], off offset:2048
	s_nop 0
	global_store_dwordx4 v[82:83], v[108:111], off offset:2048
	global_load_dwordx4 v[140:143], v[140:141], off offset:3072
	s_cbranch_execz .LBB0_3467
	s_branch .LBB0_3471

.Lxm_plain_0:
	global_load_dwordx4 v[136:139], v[82:83], off
	global_load_dwordx4 v[144:147], v[82:83], off offset:1024
	global_load_dwordx4 v[132:135], v[82:83], off offset:2048
	global_load_dwordx4 v[140:143], v[82:83], off offset:3072
	s_waitcnt vmcnt(3)
	v_pk_mul_f32 v[204:205], v[138:139], v[138:139]
	v_pk_mul_f32 v[206:207], v[136:137], v[136:137]
	s_nop 0
	v_pk_mov_b32 v[208:209], v[206:207], v[204:205] op_sel:[1,0]
	v_mov_b32_e32 v207, v205
	v_pk_add_f32 v[158:159], v[208:209], v[206:207]
	s_waitcnt vmcnt(2)
	v_pk_mul_f32 v[204:205], v[146:147], v[146:147]
	v_pk_mul_f32 v[206:207], v[144:145], v[144:145]
	s_nop 0
	v_pk_mov_b32 v[208:209], v[206:207], v[204:205] op_sel:[1,0]
	v_mov_b32_e32 v207, v205
	v_pk_add_f32 v[160:161], v[208:209], v[206:207]
	s_nop 0
	v_pk_add_f32 v[82:83], v[158:159], v[158:159] op_sel:[0,1] op_sel_hi:[1,0]
	v_pk_add_f32 v[158:159], v[160:161], v[160:161] op_sel:[0,1] op_sel_hi:[1,0]
	s_waitcnt vmcnt(0)
	v_mul_f32_e32 v80, v140, v140
	v_mul_f32_e32 v176, v141, v141
	v_mov_b32_e32 v83, v80
	v_mov_b32_e32 v159, v176
	v_mul_f32_e32 v80, v133, v133
	v_pk_add_f32 v[82:83], v[82:83], v[158:159]
	v_pk_fma_f32 v[158:159], v[132:133], v[132:133], v[80:81] op_sel_hi:[1,1,0]
	v_mul_f32_e32 v80, v135, v135
	v_mul_f32_e32 v177, v142, v142
	v_mul_f32_e32 v178, v143, v143
	v_pk_fma_f32 v[160:161], v[134:135], v[134:135], v[80:81] op_sel_hi:[1,1,0]
	v_mov_b32_e32 v159, v177
	v_mov_b32_e32 v161, v178
	v_pk_add_f32 v[158:159], v[158:159], v[160:161]
	s_nop 0
	v_pk_add_f32 v[82:83], v[82:83], v[158:159]
	s_nop 0
	v_add_f32_e32 v80, v82, v83
	ds_bpermute_b32 v82, v149, v80
	s_waitcnt lgkmcnt(0)
	v_add_f32_e32 v80, v80, v82
	ds_bpermute_b32 v82, v171, v80
	s_waitcnt lgkmcnt(0)
	v_add_f32_e32 v80, v80, v82
	ds_bpermute_b32 v82, v172, v80
	s_waitcnt lgkmcnt(0)
	v_add_f32_e32 v80, v80, v82
	ds_bpermute_b32 v82, v173, v80
	s_waitcnt lgkmcnt(0)
	v_add_f32_e32 v80, v80, v82
	ds_bpermute_b32 v82, v174, v80
	s_waitcnt lgkmcnt(0)
	v_add_f32_e32 v80, v80, v82
	ds_bpermute_b32 v82, v175, v80
	s_waitcnt lgkmcnt(0)
	v_add_f32_e32 v80, v80, v82
	v_fmamk_f32 v80, v80, 0x3a800000, v231
	v_cmp_gt_f32_e32 vcc, s48, v80
	v_mul_f32_e32 v82, 0x4f800000, v80
	s_nop 0
	v_cndmask_b32_e32 v80, v80, v82, vcc
	v_sqrt_f32_e32 v82, v80
	s_nop 0
	v_add_u32_e32 v83, -1, v82
	v_fma_f32 v158, -v83, v82, v80
	v_cmp_ge_f32_e64 s[42:43], 0, v158
	v_add_u32_e32 v158, 1, v82
	s_nop 0
	v_cndmask_b32_e64 v83, v82, v83, s[42:43]
	v_fma_f32 v82, -v158, v82, v80
	v_cmp_lt_f32_e64 s[42:43], 0, v82
	s_nop 1
	v_cndmask_b32_e64 v82, v83, v158, s[42:43]
	v_mul_f32_e32 v83, 0x37800000, v82
	v_cndmask_b32_e32 v82, v82, v83, vcc
	v_cmp_class_f32_e32 vcc, v80, v230
	s_nop 1
	v_cndmask_b32_e32 v80, v82, v80, vcc
	v_div_scale_f32 v82, s[26:27], v80, v80, 1.0
	v_rcp_f32_e32 v83, v82
	s_nop 0
	v_fma_f32 v158, -v82, v83, 1.0
	v_fmac_f32_e32 v83, v158, v83
	v_div_scale_f32 v158, vcc, 1.0, v80, 1.0
	v_mul_f32_e32 v159, v158, v83
	v_fma_f32 v160, -v82, v159, v158
	v_fmac_f32_e32 v159, v160, v83
	v_fma_f32 v82, -v82, v159, v158
	v_div_fmas_f32 v82, v82, v83, v159
	v_div_fixup_f32 v80, v82, v80, 1.0
	v_pk_mul_f32 v[82:83], v[136:137], v[80:81] op_sel_hi:[1,0]
	v_pk_mul_f32 v[136:137], v[138:139], v[80:81] op_sel_hi:[1,0]
	s_nop 0
	v_pk_mul_f32 v[138:139], v[118:119], v[136:137]
	v_pk_mul_f32 v[136:137], v[116:117], v[82:83]
	v_pk_mul_f32 v[82:83], v[144:145], v[80:81] op_sel_hi:[1,0]
	v_pk_mul_f32 v[116:117], v[146:147], v[80:81] op_sel_hi:[1,0]
	v_pk_mul_f32 v[144:145], v[120:121], v[82:83]
	v_pk_mul_f32 v[146:147], v[122:123], v[116:117]
	v_pk_mul_f32 v[82:83], v[132:133], v[80:81] op_sel_hi:[1,0]
	v_pk_mul_f32 v[116:117], v[134:135], v[80:81] op_sel_hi:[1,0]
	v_pk_mul_f32 v[132:133], v[128:129], v[82:83]
	v_pk_mul_f32 v[134:135], v[130:131], v[116:117]
	v_pk_mul_f32 v[82:83], v[140:141], v[80:81] op_sel_hi:[1,0]
	v_pk_mul_f32 v[116:117], v[142:143], v[80:81] op_sel_hi:[1,0]
	v_pk_mul_f32 v[140:141], v[124:125], v[82:83]
	v_pk_mul_f32 v[142:143], v[126:127], v[116:117]
	s_cmpk_lg_i32 s7, 0xc78f
	s_cbranch_scc1 .LBB0_3470

.LBB0_4248:
	v_lshl_add_u64 v[0:1], s[78:79], 0, v[40:41]
	v_lshl_add_u64 v[46:47], s[78:79], 0, v[42:43]
	s_mov_b64 s[6:7], 0x15886000
	global_load_dword v48, v[0:1], off
	v_lshl_add_u64 v[0:1], v[46:47], 0, s[6:7]
	v_add_co_u32_e32 v2, vcc, 0x15886000, v46
	v_lshl_add_u64 v[32:33], s[78:79], 0, v[44:45]
	s_mov_b64 s[6:7], 0x274e6000
	v_addc_co_u32_e32 v3, vcc, 0, v47, vcc
	v_lshl_add_u64 v[16:17], v[32:33], 0, s[6:7]
	s_mov_b32 s6, 0x274e6000
	v_add_co_u32_e32 v4, vcc, s6, v32
	global_load_dwordx4 v[8:11], v[2:3], off
	s_nop 0
	global_load_dwordx4 v[0:3], v[0:1], off offset:16
	v_addc_co_u32_e32 v5, vcc, 0, v33, vcc
	global_load_dwordx4 v[20:23], v[4:5], off
	s_nop 0
	global_load_dwordx4 v[4:7], v[16:17], off offset:48
	global_load_dwordx4 v[12:15], v[16:17], off offset:32
	s_nop 0
	global_load_dwordx4 v[16:19], v[16:17], off offset:16
	s_add_i32 s5, s5, s12
	v_lshl_add_u64 v[40:41], v[40:41], 0, s[18:19]
	v_lshl_add_u64 v[42:43], v[42:43], 0, s[26:27]
	v_lshl_add_u64 v[44:45], v[44:45], 0, s[38:39]
	s_cmpk_gt_i32 s5, 0x40ff
	s_waitcnt vmcnt(5)
	v_lshlrev_b32_e32 v54, 16, v8
	s_waitcnt vmcnt(3)
	v_mov_b32_e32 v24, v21
	v_mov_b32_e32 v25, v22
	v_mov_b32_e32 v26, v20
	v_mov_b32_e32 v27, v23
	v_pk_add_f32 v[24:25], v[24:25], v[26:27]
	s_waitcnt vmcnt(0)
	v_mov_b32_e32 v26, v17
	v_mov_b32_e32 v27, v18
	v_mov_b32_e32 v28, v16
	v_mov_b32_e32 v29, v19
	v_pk_add_f32 v[26:27], v[26:27], v[28:29]
	v_add_f32_e32 v24, v24, v25
	v_pk_add_f32 v[26:27], v[26:27], v[26:27] op_sel:[0,1] op_sel_hi:[1,0]
	v_add_f32_e32 v24, 0, v24
	v_add_f32_e32 v28, v12, v13
	v_add_f32_e32 v30, v14, v15
	v_mov_b32_e32 v25, v4
	v_mov_b32_e32 v27, v5
	v_mov_b32_e32 v29, v6
	v_mov_b32_e32 v31, v7
	v_pk_add_f32 v[24:25], v[24:25], v[26:27]
	v_pk_add_f32 v[26:27], v[28:29], v[30:31]
	v_and_b32_e32 v55, 0xffff0000, v8
	v_pk_add_f32 v[24:25], v[24:25], v[26:27]
	v_lshlrev_b32_e32 v8, 16, v9
	v_add_f32_e32 v24, v24, v25
	v_and_b32_e32 v9, 0xffff0000, v9
	s_nop 0
	v_add_f32_dpp v24, v24, v24 quad_perm:[1,0,3,2] row_mask:0xf bank_mask:0xf bound_ctrl:1
	s_nop 1
	v_add_f32_dpp v34, v24, v24 quad_perm:[2,3,0,1] row_mask:0xf bank_mask:0xf bound_ctrl:1
	v_fmamk_f32 v21, v34, 0xbc800000, v21
	v_fmamk_f32 v20, v34, 0xbc800000, v20
	v_fmamk_f32 v23, v34, 0xbc800000, v23
	v_fmac_f32_e32 v22, 0xbc800000, v34
	v_pk_mul_f32 v[24:25], v[22:23], v[22:23]
	v_pk_mul_f32 v[26:27], v[20:21], v[20:21]
	v_fmamk_f32 v17, v34, 0xbc800000, v17
	v_pk_mov_b32 v[28:29], v[26:27], v[24:25] op_sel:[1,0]
	v_mov_b32_e32 v27, v25
	v_fmamk_f32 v16, v34, 0xbc800000, v16
	v_fmamk_f32 v19, v34, 0xbc800000, v19
	v_fmac_f32_e32 v18, 0xbc800000, v34
	v_pk_add_f32 v[24:25], v[28:29], v[26:27]
	v_pk_mul_f32 v[26:27], v[18:19], v[18:19]
	v_pk_mul_f32 v[28:29], v[16:17], v[16:17]
	v_fmamk_f32 v5, v34, 0xbc800000, v5
	v_pk_mov_b32 v[30:31], v[28:29], v[26:27] op_sel:[1,0]
	v_mov_b32_e32 v29, v27
	v_pk_add_f32 v[26:27], v[30:31], v[28:29]
	v_fmac_f32_e32 v4, 0xbc800000, v34
	v_mul_f32_e32 v28, v4, v4
	v_mul_f32_e32 v29, v5, v5
	v_pk_add_f32 v[24:25], v[24:25], v[24:25] op_sel:[0,1] op_sel_hi:[1,0]
	v_pk_add_f32 v[26:27], v[26:27], v[26:27] op_sel:[0,1] op_sel_hi:[1,0]
	v_fmamk_f32 v13, v34, 0xbc800000, v13
	v_fmamk_f32 v15, v34, 0xbc800000, v15
	v_mov_b32_e32 v25, v28
	v_mov_b32_e32 v27, v29
	v_fmamk_f32 v12, v34, 0xbc800000, v12
	v_fmac_f32_e32 v14, 0xbc800000, v34
	v_fmamk_f32 v7, v34, 0xbc800000, v7
	v_fmamk_f32 v6, v34, 0xbc800000, v6
	v_pk_add_f32 v[24:25], v[24:25], v[26:27]
	v_mul_f32_e32 v26, v13, v13
	v_mul_f32_e32 v28, v15, v15
	v_mul_f32_e32 v30, v6, v6
	v_mul_f32_e32 v31, v7, v7
	v_pk_fma_f32 v[26:27], v[12:13], v[12:13], v[26:27] op_sel_hi:[1,1,0]
	v_pk_fma_f32 v[28:29], v[14:15], v[14:15], v[28:29] op_sel_hi:[1,1,0]
	v_mov_b32_e32 v27, v30
	v_mov_b32_e32 v29, v31
	v_pk_add_f32 v[26:27], v[26:27], v[28:29]
	s_nop 0
	v_pk_add_f32 v[24:25], v[24:25], v[26:27]
	s_nop 0
	v_add_f32_e32 v24, v24, v25
	v_mov_b32_e32 v25, 0x3a27c5ac
	s_nop 0
	v_add_f32_dpp v24, v24, v24 quad_perm:[1,0,3,2] row_mask:0xf bank_mask:0xf bound_ctrl:1
	s_nop 1
	v_add_f32_dpp v24, v24, v24 quad_perm:[2,3,0,1] row_mask:0xf bank_mask:0xf bound_ctrl:1
	v_fmamk_f32 v24, v24, 0x3c800000, v25
	v_cmp_gt_f32_e32 vcc, s13, v24
	v_mul_f32_e32 v25, 0x4f800000, v24
	s_nop 0
	v_cndmask_b32_e32 v24, v24, v25, vcc
	v_sqrt_f32_e32 v25, v24
	s_nop 0
	v_add_u32_e32 v26, -1, v25
	v_fma_f32 v27, -v26, v25, v24
	v_cmp_ge_f32_e64 s[42:43], 0, v27
	v_add_u32_e32 v27, 1, v25
	s_nop 0
	v_cndmask_b32_e64 v26, v25, v26, s[42:43]
	v_fma_f32 v25, -v27, v25, v24
	v_cmp_lt_f32_e64 s[42:43], 0, v25
	s_nop 1
	v_cndmask_b32_e64 v25, v26, v27, s[42:43]
	v_mul_f32_e32 v26, 0x37800000, v25
	v_cndmask_b32_e32 v25, v25, v26, vcc
	v_cmp_class_f32_e32 vcc, v24, v230
	s_nop 1
	v_cndmask_b32_e32 v24, v25, v24, vcc
	v_div_scale_f32 v25, s[6:7], v24, v24, 1.0
	v_rcp_f32_e32 v26, v25
	s_mov_b32 s6, 0x21b86000
	v_fma_f32 v27, -v25, v26, 1.0
	v_fmac_f32_e32 v26, v27, v26
	v_div_scale_f32 v27, vcc, 1.0, v24, 1.0
	v_mul_f32_e32 v28, v27, v26
	v_fma_f32 v29, -v25, v28, v27
	v_fmac_f32_e32 v28, v29, v26
	v_fma_f32 v25, -v25, v28, v27
	v_div_fmas_f32 v25, v25, v26, v28
	v_add_co_u32_e32 v52, vcc, s6, v32
	v_div_fixup_f32 v50, v25, v24, 1.0
	global_load_dwordx4 v[24:27], v[36:37], off
	global_load_dwordx4 v[28:31], v[38:39], off
	v_addc_co_u32_e32 v53, vcc, 0, v33, vcc
	global_load_dwordx4 v[32:35], v[52:53], off
	global_load_dwordx4 v[84:87], v[36:37], off offset:16
	global_load_dwordx4 v[88:91], v[38:39], off offset:16
	global_load_dwordx4 v[92:95], v[52:53], off offset:16
	global_load_dwordx4 v[96:99], v[36:37], off offset:32
	global_load_dwordx4 v[100:103], v[38:39], off offset:32
	global_load_dwordx4 v[104:107], v[52:53], off offset:32
	global_load_dwordx4 v[108:111], v[36:37], off offset:48
	global_load_dwordx4 v[112:115], v[38:39], off offset:48
	global_load_dwordx4 v[116:119], v[52:53], off offset:48
	v_pk_mul_f32 v[20:21], v[50:51], v[20:21] op_sel_hi:[0,1]
	v_pk_mul_f32 v[22:23], v[50:51], v[22:23] op_sel_hi:[0,1]
	v_pk_mul_f32 v[16:17], v[50:51], v[16:17] op_sel_hi:[0,1]
	v_pk_mul_f32 v[18:19], v[50:51], v[18:19] op_sel_hi:[0,1]
	v_pk_mul_f32 v[12:13], v[50:51], v[12:13] op_sel_hi:[0,1]
	v_pk_mul_f32 v[14:15], v[50:51], v[14:15] op_sel_hi:[0,1]
	v_pk_mul_f32 v[4:5], v[50:51], v[4:5] op_sel_hi:[0,1]
	v_pk_mul_f32 v[6:7], v[50:51], v[6:7] op_sel_hi:[0,1]
	s_waitcnt vmcnt(10)
	v_pk_fma_f32 v[22:23], v[26:27], v[22:23], v[30:31]
	v_pk_fma_f32 v[20:21], v[24:25], v[20:21], v[28:29]
	s_waitcnt vmcnt(9)
	v_pk_fma_f32 v[22:23], v[48:49], v[34:35], v[22:23] op_sel_hi:[0,1,1]
	v_pk_fma_f32 v[20:21], v[48:49], v[32:33], v[20:21] op_sel_hi:[0,1,1]
	v_pk_mul_f32 v[22:23], v[22:23], v[8:9]
	v_pk_mul_f32 v[8:9], v[20:21], v[54:55]
	v_lshlrev_b32_e32 v32, 16, v10
	v_cvt_pk_bf16_f32 v8, v8, v9
	v_cvt_pk_bf16_f32 v9, v22, v23
	s_waitcnt vmcnt(6)
	v_mov_b64_e32 v[20:21], v[84:85]
	v_mov_b64_e32 v[22:23], v[86:87]
	v_mov_b64_e32 v[24:25], v[88:89]
	v_mov_b64_e32 v[26:27], v[90:91]
	v_mov_b64_e32 v[28:29], v[92:93]
	v_mov_b64_e32 v[30:31], v[94:95]
	v_and_b32_e32 v33, 0xffff0000, v10
	v_lshlrev_b32_e32 v10, 16, v11
	v_and_b32_e32 v11, 0xffff0000, v11
	s_nop 0
	v_pk_fma_f32 v[18:19], v[22:23], v[18:19], v[26:27]
	v_pk_fma_f32 v[16:17], v[20:21], v[16:17], v[24:25]
	s_nop 0
	v_pk_fma_f32 v[18:19], v[48:49], v[30:31], v[18:19] op_sel_hi:[0,1,1]
	v_pk_fma_f32 v[16:17], v[48:49], v[28:29], v[16:17] op_sel_hi:[0,1,1]
	v_pk_mul_f32 v[18:19], v[18:19], v[10:11]
	v_pk_mul_f32 v[10:11], v[16:17], v[32:33]
	v_lshlrev_b32_e32 v28, 16, v0
	v_cvt_pk_bf16_f32 v10, v10, v11
	v_cvt_pk_bf16_f32 v11, v18, v19
	s_waitcnt vmcnt(3)
	v_mov_b64_e32 v[16:17], v[96:97]
	v_mov_b64_e32 v[18:19], v[98:99]
	v_mov_b64_e32 v[20:21], v[100:101]
	v_mov_b64_e32 v[22:23], v[102:103]
	v_mov_b64_e32 v[24:25], v[104:105]
	v_mov_b64_e32 v[26:27], v[106:107]
	v_and_b32_e32 v29, 0xffff0000, v0
	v_lshlrev_b32_e32 v0, 16, v1
	v_and_b32_e32 v1, 0xffff0000, v1
	s_nop 0
	v_pk_fma_f32 v[14:15], v[18:19], v[14:15], v[22:23]
	v_pk_fma_f32 v[12:13], v[16:17], v[12:13], v[20:21]
	s_nop 0
	v_pk_fma_f32 v[14:15], v[48:49], v[26:27], v[14:15] op_sel_hi:[0,1,1]
	v_pk_fma_f32 v[12:13], v[48:49], v[24:25], v[12:13] op_sel_hi:[0,1,1]
	v_pk_mul_f32 v[14:15], v[14:15], v[0:1]
	v_pk_mul_f32 v[0:1], v[12:13], v[28:29]
	v_lshlrev_b32_e32 v24, 16, v2
	v_cvt_pk_bf16_f32 v0, v0, v1
	v_cvt_pk_bf16_f32 v1, v14, v15
	s_waitcnt vmcnt(0)
	v_mov_b64_e32 v[12:13], v[108:109]
	v_mov_b64_e32 v[14:15], v[110:111]
	v_mov_b64_e32 v[16:17], v[112:113]
	v_mov_b64_e32 v[18:19], v[114:115]
	v_mov_b64_e32 v[20:21], v[116:117]
	v_mov_b64_e32 v[22:23], v[118:119]
	v_and_b32_e32 v25, 0xffff0000, v2
	v_lshlrev_b32_e32 v2, 16, v3
	v_and_b32_e32 v3, 0xffff0000, v3
	s_nop 0
	v_pk_fma_f32 v[6:7], v[14:15], v[6:7], v[18:19]
	v_pk_fma_f32 v[4:5], v[12:13], v[4:5], v[16:17]
	s_nop 0
	v_pk_fma_f32 v[6:7], v[48:49], v[22:23], v[6:7] op_sel_hi:[0,1,1]
	v_pk_fma_f32 v[4:5], v[48:49], v[20:21], v[4:5] op_sel_hi:[0,1,1]
	v_pk_mul_f32 v[6:7], v[6:7], v[2:3]
	v_pk_mul_f32 v[2:3], v[4:5], v[24:25]
	v_add_co_u32_e32 v4, vcc, 0x2b5e6000, v46
	v_cvt_pk_bf16_f32 v2, v2, v3
	v_cvt_pk_bf16_f32 v3, v6, v7
	s_nop 1
	v_addc_co_u32_e32 v5, vcc, 0, v47, vcc
	global_store_dwordx4 v[4:5], v[8:11], off
	global_store_dwordx4 v[4:5], v[0:3], off offset:16
	s_cbranch_scc0 .LBB0_4248
	s_branch .LBB0_4245
